# rwkv_seq v3 + staggered VMEM issue: waves 0-3 issue y store and LDS-DMA right after the barrier, waves 4-7 at the end of the chunk step
# speedup vs baseline: 1.0017x; 1.0011x over previous
; #define LAS __attribute__((address_space(3)))
; __device__ __forceinline__ void lds_barrier() { asm volatile("s_waitcnt lgkmcnt(0)" ::: "memory"); __builtin_amdgcn_s_barrier(); asm volatile("" ::: "memory"); }
; __device__ __forceinline__ void rwkv_seq(LAS unsigned char* lds, const MixBufs& B, const bf16_t* rq, int L, int seq, int h, int d) {
;     ...
;     for (int c = 0; c < nch; ++c) {
;         const bf16_t* gn = g + (c + 1 < nch ? custride : 0);
;         const bf16x8 nqa0 = *(const bf16x8*)(gn + aoff), nqa1 = *(const bf16x8*)(gn + aoff + 32);
;         const bf16x8 npa0 = *(const bf16x8*)(gn + 4096 + aoff), npa1 = *(const bf16x8*)(gn + 4096 + aoff + 32);
;         const u32x2 nhl0 = *(const u32x2*)(gn + 8192 + (tn0 * 16 + r) * 64 + tm * 16 + q * 4), nhl1 = *(const u32x2*)(gn + 8192 + ((tn0 + 1) * 16 + r) * 64 + tm * 16 + q * 4);
;         u32x2 yl[2];
;         const int ti_ = tm * 16 + r;
;         bf16_t* yrow = yout + (size_t)(d == 0 ? base + c * 64 + ti_ : base + L - 1 - (c * 64 + ti_)) * 256 + h * 64 + q * 4;
; #pragma unroll
;         for (int tt = 0; tt < 2; ++tt) yl[tt] = *(const u32x2*)(yrow + (tn0 + tt) * 16);
;         lds_barrier();
;         const LAS bf16_t* cur = (const LAS bf16_t*)(lds + (c & 1) * 9216);
;         LAS bf16_t* nxt = (LAS bf16_t*)(lds + ((c + 1) & 1) * 9216);
; #pragma unroll
;         for (int tt = 0; tt < 2; ++tt) {
;             const int tn = tn0 + tt;
;             const bf16x8 b0 = *(const LAS bf16x8*)(cur + (tn * 16 + r) * RL + q * 8), b1 = *(const LAS bf16x8*)(cur + (tn * 16 + r) * RL + 32 + q * 8);
.Lrws3_gen_loop:
	s_waitcnt vmcnt(5)
	s_waitcnt lgkmcnt(0)
	s_barrier
	ds_read_b128 v[72:75], v4 offset:16384
	ds_read_b128 v[8:11], v6 offset:0
	ds_read_b128 v[48:51], v45 offset:0
	ds_read_b128 v[56:59], v45 offset:8192
	ds_read_b128 v[12:15], v6 offset:64
	ds_read_b128 v[60:63], v46 offset:8192
	ds_read_b128 v[52:55], v46 offset:0
	ds_read_b128 v[16:19], v6 offset:2304
	ds_read_b128 v[20:23], v6 offset:2368
	ds_read_b64 v[64:65], v47 offset:0
	ds_read_b64 v[66:67], v47 offset:2048
	ds_read_b64 v[68:69], v5 offset:0
	ds_read_b64 v[70:71], v44 offset:0
	s_movk_i32 s42, 0
	s_cmp_lt_u32 s4, 4
	s_cbranch_scc0 .Lrws3_gen_late0
	s_waitcnt lgkmcnt(12)
	s_cmp_eq_u32 s16, s64
	s_cbranch_scc1 .Lrws3_gen_skipst0
	global_store_dwordx4 v3, v[72:75], s[6:7]
	s_add_u32 s6, s6, s48
	s_addc_u32 s7, s7, s49

; #define LAS __attribute__((address_space(3)))
; __device__ __forceinline__ unsigned pk2(float lo, float hi) { f32x2 f = {lo, hi}; bf16x2_t v = __builtin_convertvector(f, bf16x2_t); return __builtin_bit_cast(unsigned, v); }
; __device__ __forceinline__ void rwkv_seq(LAS unsigned char* lds, const MixBufs& B, const bf16_t* rq, int L, int seq, int h, int d) {
;     ...
;         for (int tt = 0; tt < 2; ++tt) {
;             const int tn = tn0 + tt;
;             const bf16x8 b0 = *(const LAS bf16x8*)(cur + (tn * 16 + r) * RL + q * 8), b1 = *(const LAS bf16x8*)(cur + (tn * 16 + r) * RL + 32 + q * 8);
;             f32x4 y = (f32x4){0.f, 0.f, 0.f, 0.f}, hn = (f32x4){0.f, 0.f, 0.f, 0.f};
;             y = __builtin_amdgcn_mfma_f32_16x16x32_bf16(b0, qa0, y, 0, 0, 0); y = __builtin_amdgcn_mfma_f32_16x16x32_bf16(b1, qa1, y, 0, 0, 0);
;             hn = __builtin_amdgcn_mfma_f32_16x16x32_bf16(pa0, b0, hn, 0, 0, 0); hn = __builtin_amdgcn_mfma_f32_16x16x32_bf16(pa1, b1, hn, 0, 0, 0);
;             const u32x2 hl = tt == 0 ? hl0 : hl1;
;             hn[0] += __uint_as_float(hl.x << 16); hn[1] += __uint_as_float(hl.x & 0xffff0000u); hn[2] += __uint_as_float(hl.y << 16); hn[3] += __uint_as_float(hl.y & 0xffff0000u);
;             u32x2 o; o.x = pk2(hn[0], hn[1]); o.y = pk2(hn[2], hn[3]);
;             *(LAS u32x2*)(nxt + (tn * 16 + r) * RL + tm * 16 + q * 4) = o;
;             { const u32x2 yo = yl[tt];
;               y[0] += __uint_as_float(yo.x << 16); y[1] += __uint_as_float(yo.x & 0xffff0000u); y[2] += __uint_as_float(yo.y << 16); y[3] += __uint_as_float(yo.y & 0xffff0000u);
;               u32x2 o2; o2.x = pk2(y[0], y[1]); o2.y = pk2(y[2], y[3]); *(u32x2*)(yrow + tn * 16) = o2; }
.Lrws3_gen_late0:
	s_waitcnt lgkmcnt(9)
	v_mfma_f32_16x16x32_bf16 v[24:27], v[8:11], v[48:51], 0
	v_mfma_f32_16x16x32_bf16 v[28:31], v[56:59], v[8:11], 0
	s_waitcnt lgkmcnt(6)
	v_mfma_f32_16x16x32_bf16 v[28:31], v[60:63], v[12:15], v[28:31]
	v_mfma_f32_16x16x32_bf16 v[24:27], v[12:15], v[52:55], v[24:27]
	s_waitcnt lgkmcnt(5)
	v_mfma_f32_16x16x32_bf16 v[36:39], v[56:59], v[16:19], 0
	v_mfma_f32_16x16x32_bf16 v[32:35], v[16:19], v[48:51], 0
	s_waitcnt lgkmcnt(4)
	v_mfma_f32_16x16x32_bf16 v[36:39], v[60:63], v[20:23], v[36:39]
	v_mfma_f32_16x16x32_bf16 v[32:35], v[20:23], v[52:55], v[32:35]
	s_waitcnt lgkmcnt(0)
	v_lshlrev_b32_e32 v40, 16, v64
	v_and_b32_e32 v41, 0xffff0000, v64
	v_lshlrev_b32_e32 v42, 16, v65
	v_and_b32_e32 v43, 0xffff0000, v65
	v_pk_add_f32 v[28:29], v[28:29], v[40:41]
	v_pk_add_f32 v[30:31], v[30:31], v[42:43]
	v_cvt_pk_bf16_f32 v28, v28, v29
	v_cvt_pk_bf16_f32 v29, v30, v31
	ds_write_b64 v7, v[28:29] offset:9216
	v_lshlrev_b32_e32 v40, 16, v66
	v_and_b32_e32 v41, 0xffff0000, v66
	v_lshlrev_b32_e32 v42, 16, v67
	v_and_b32_e32 v43, 0xffff0000, v67
	v_pk_add_f32 v[36:37], v[36:37], v[40:41]
	v_pk_add_f32 v[38:39], v[38:39], v[42:43]
	v_cvt_pk_bf16_f32 v36, v36, v37
	v_cvt_pk_bf16_f32 v37, v38, v39
	ds_write_b64 v7, v[36:37] offset:11520
	v_lshlrev_b32_e32 v40, 16, v68
	v_and_b32_e32 v41, 0xffff0000, v68
	v_lshlrev_b32_e32 v42, 16, v69
	v_and_b32_e32 v43, 0xffff0000, v69
	v_pk_add_f32 v[24:25], v[24:25], v[40:41]
	v_pk_add_f32 v[26:27], v[26:27], v[42:43]
	v_cvt_pk_bf16_f32 v24, v24, v25
	v_cvt_pk_bf16_f32 v25, v26, v27
	ds_write_b64 v5, v[24:25] offset:0
	v_lshlrev_b32_e32 v40, 16, v70
	v_and_b32_e32 v41, 0xffff0000, v70
	v_lshlrev_b32_e32 v42, 16, v71
	v_and_b32_e32 v43, 0xffff0000, v71
	v_pk_add_f32 v[32:33], v[32:33], v[40:41]
	v_pk_add_f32 v[34:35], v[34:35], v[42:43]
	v_cvt_pk_bf16_f32 v32, v32, v33
	v_cvt_pk_bf16_f32 v33, v34, v35
	ds_write_b64 v44, v[32:33] offset:0
	s_cmp_lt_u32 s4, 4
	s_cbranch_scc1 .Lrws3_gen_end0
	s_cmp_eq_u32 s16, s64
	s_cbranch_scc1 .Lrws3_gen_skipst20
	global_store_dwordx4 v3, v[72:75], s[6:7]
	s_add_u32 s6, s6, s48
	s_addc_u32 s7, s7, s49

; #define LAS __attribute__((address_space(3)))
; __device__ __forceinline__ void lds_barrier() { asm volatile("s_waitcnt lgkmcnt(0)" ::: "memory"); __builtin_amdgcn_s_barrier(); asm volatile("" ::: "memory"); }
; __device__ __forceinline__ void rwkv_seq(LAS unsigned char* lds, const MixBufs& B, const bf16_t* rq, int L, int seq, int h, int d) {
;     ...
;         for (int tt = 0; tt < 2; ++tt) yl[tt] = *(const u32x2*)(yrow + (tn0 + tt) * 16);
;         lds_barrier();
;         const LAS bf16_t* cur = (const LAS bf16_t*)(lds + (c & 1) * 9216);
;         LAS bf16_t* nxt = (LAS bf16_t*)(lds + ((c + 1) & 1) * 9216);
; #pragma unroll
;         for (int tt = 0; tt < 2; ++tt) {
;             const int tn = tn0 + tt;
;             const bf16x8 b0 = *(const LAS bf16x8*)(cur + (tn * 16 + r) * RL + q * 8), b1 = *(const LAS bf16x8*)(cur + (tn * 16 + r) * RL + 32 + q * 8);
.Lrws3_gen_end0:
	s_add_i32 s16, s16, -1
	s_cmp_eq_u32 s16, 0
	s_cbranch_scc1 .Lrws3_gen_exit
	s_waitcnt vmcnt(5)
	s_waitcnt lgkmcnt(0)
	s_barrier
	ds_read_b128 v[72:75], v4 offset:0
	ds_read_b128 v[8:11], v6 offset:9216
	ds_read_b128 v[48:51], v45 offset:24576
	ds_read_b128 v[56:59], v45 offset:32768
	ds_read_b128 v[12:15], v6 offset:9280
	ds_read_b128 v[60:63], v46 offset:32768
	ds_read_b128 v[52:55], v46 offset:24576
	ds_read_b128 v[16:19], v6 offset:11520
	ds_read_b128 v[20:23], v6 offset:11584
	ds_read_b64 v[64:65], v47 offset:24576
	ds_read_b64 v[66:67], v47 offset:26624
	ds_read_b64 v[68:69], v5 offset:8192
	ds_read_b64 v[70:71], v44 offset:8192
	s_movk_i32 s42, 8192
	s_cmp_lt_u32 s4, 4
	s_cbranch_scc0 .Lrws3_gen_late1
	s_waitcnt lgkmcnt(12)
	s_cmp_eq_u32 s16, s64
	s_cbranch_scc1 .Lrws3_gen_skipst1
	global_store_dwordx4 v3, v[72:75], s[6:7]
	s_add_u32 s6, s6, s48
	s_addc_u32 s7, s7, s49

; #define LAS __attribute__((address_space(3)))
; __device__ __forceinline__ unsigned pk2(float lo, float hi) { f32x2 f = {lo, hi}; bf16x2_t v = __builtin_convertvector(f, bf16x2_t); return __builtin_bit_cast(unsigned, v); }
; __device__ __forceinline__ void rwkv_seq(LAS unsigned char* lds, const MixBufs& B, const bf16_t* rq, int L, int seq, int h, int d) {
;     ...
;         for (int tt = 0; tt < 2; ++tt) {
;             const int tn = tn0 + tt;
;             const bf16x8 b0 = *(const LAS bf16x8*)(cur + (tn * 16 + r) * RL + q * 8), b1 = *(const LAS bf16x8*)(cur + (tn * 16 + r) * RL + 32 + q * 8);
;             f32x4 y = (f32x4){0.f, 0.f, 0.f, 0.f}, hn = (f32x4){0.f, 0.f, 0.f, 0.f};
;             y = __builtin_amdgcn_mfma_f32_16x16x32_bf16(b0, qa0, y, 0, 0, 0); y = __builtin_amdgcn_mfma_f32_16x16x32_bf16(b1, qa1, y, 0, 0, 0);
;             hn = __builtin_amdgcn_mfma_f32_16x16x32_bf16(pa0, b0, hn, 0, 0, 0); hn = __builtin_amdgcn_mfma_f32_16x16x32_bf16(pa1, b1, hn, 0, 0, 0);
;             const u32x2 hl = tt == 0 ? hl0 : hl1;
;             hn[0] += __uint_as_float(hl.x << 16); hn[1] += __uint_as_float(hl.x & 0xffff0000u); hn[2] += __uint_as_float(hl.y << 16); hn[3] += __uint_as_float(hl.y & 0xffff0000u);
;             u32x2 o; o.x = pk2(hn[0], hn[1]); o.y = pk2(hn[2], hn[3]);
;             *(LAS u32x2*)(nxt + (tn * 16 + r) * RL + tm * 16 + q * 4) = o;
;             { const u32x2 yo = yl[tt];
;               y[0] += __uint_as_float(yo.x << 16); y[1] += __uint_as_float(yo.x & 0xffff0000u); y[2] += __uint_as_float(yo.y << 16); y[3] += __uint_as_float(yo.y & 0xffff0000u);
;               u32x2 o2; o2.x = pk2(y[0], y[1]); o2.y = pk2(y[2], y[3]); *(u32x2*)(yrow + tn * 16) = o2; }
.Lrws3_gen_late1:
	s_waitcnt lgkmcnt(9)
	v_mfma_f32_16x16x32_bf16 v[24:27], v[8:11], v[48:51], 0
	v_mfma_f32_16x16x32_bf16 v[28:31], v[56:59], v[8:11], 0
	s_waitcnt lgkmcnt(6)
	v_mfma_f32_16x16x32_bf16 v[28:31], v[60:63], v[12:15], v[28:31]
	v_mfma_f32_16x16x32_bf16 v[24:27], v[12:15], v[52:55], v[24:27]
	s_waitcnt lgkmcnt(5)
	v_mfma_f32_16x16x32_bf16 v[36:39], v[56:59], v[16:19], 0
	v_mfma_f32_16x16x32_bf16 v[32:35], v[16:19], v[48:51], 0
	s_waitcnt lgkmcnt(4)
	v_mfma_f32_16x16x32_bf16 v[36:39], v[60:63], v[20:23], v[36:39]
	v_mfma_f32_16x16x32_bf16 v[32:35], v[20:23], v[52:55], v[32:35]
	s_waitcnt lgkmcnt(0)
	v_lshlrev_b32_e32 v40, 16, v64
	v_and_b32_e32 v41, 0xffff0000, v64
	v_lshlrev_b32_e32 v42, 16, v65
	v_and_b32_e32 v43, 0xffff0000, v65
	v_pk_add_f32 v[28:29], v[28:29], v[40:41]
	v_pk_add_f32 v[30:31], v[30:31], v[42:43]
	v_cvt_pk_bf16_f32 v28, v28, v29
	v_cvt_pk_bf16_f32 v29, v30, v31
	ds_write_b64 v7, v[28:29] offset:18432
	v_lshlrev_b32_e32 v40, 16, v66
	v_and_b32_e32 v41, 0xffff0000, v66
	v_lshlrev_b32_e32 v42, 16, v67
	v_and_b32_e32 v43, 0xffff0000, v67
	v_pk_add_f32 v[36:37], v[36:37], v[40:41]
	v_pk_add_f32 v[38:39], v[38:39], v[42:43]
	v_cvt_pk_bf16_f32 v36, v36, v37
	v_cvt_pk_bf16_f32 v37, v38, v39
	ds_write_b64 v7, v[36:37] offset:20736
	v_lshlrev_b32_e32 v40, 16, v68
	v_and_b32_e32 v41, 0xffff0000, v68
	v_lshlrev_b32_e32 v42, 16, v69
	v_and_b32_e32 v43, 0xffff0000, v69
	v_pk_add_f32 v[24:25], v[24:25], v[40:41]
	v_pk_add_f32 v[26:27], v[26:27], v[42:43]
	v_cvt_pk_bf16_f32 v24, v24, v25
	v_cvt_pk_bf16_f32 v25, v26, v27
	ds_write_b64 v5, v[24:25] offset:8192
	v_lshlrev_b32_e32 v40, 16, v70
	v_and_b32_e32 v41, 0xffff0000, v70
	v_lshlrev_b32_e32 v42, 16, v71
	v_and_b32_e32 v43, 0xffff0000, v71
	v_pk_add_f32 v[32:33], v[32:33], v[40:41]
	v_pk_add_f32 v[34:35], v[34:35], v[42:43]
	v_cvt_pk_bf16_f32 v32, v32, v33
	v_cvt_pk_bf16_f32 v33, v34, v35
	ds_write_b64 v44, v[32:33] offset:8192
	s_cmp_lt_u32 s4, 4
	s_cbranch_scc1 .Lrws3_gen_end1
	s_cmp_eq_u32 s16, s64
	s_cbranch_scc1 .Lrws3_gen_skipst21
	global_store_dwordx4 v3, v[72:75], s[6:7]
	s_add_u32 s6, s6, s48
	s_addc_u32 s7, s7, s49

; #define LAS __attribute__((address_space(3)))
; __device__ __forceinline__ void lds_barrier() { asm volatile("s_waitcnt lgkmcnt(0)" ::: "memory"); __builtin_amdgcn_s_barrier(); asm volatile("" ::: "memory"); }
; __device__ __forceinline__ void rwkv_seq(LAS unsigned char* lds, const MixBufs& B, const bf16_t* rq, int L, int seq, int h, int d) {
;     ...
;         for (int tt = 0; tt < 2; ++tt) yl[tt] = *(const u32x2*)(yrow + (tn0 + tt) * 16);
;         lds_barrier();
;         const LAS bf16_t* cur = (const LAS bf16_t*)(lds + (c & 1) * 9216);
;         LAS bf16_t* nxt = (LAS bf16_t*)(lds + ((c + 1) & 1) * 9216);
; #pragma unroll
;         for (int tt = 0; tt < 2; ++tt) {
;             const int tn = tn0 + tt;
;             const bf16x8 b0 = *(const LAS bf16x8*)(cur + (tn * 16 + r) * RL + q * 8), b1 = *(const LAS bf16x8*)(cur + (tn * 16 + r) * RL + 32 + q * 8);
.Lrws3_gen_end1:
	s_add_i32 s16, s16, -1
	s_cmp_eq_u32 s16, 0
	s_cbranch_scc1 .Lrws3_gen_exit
	s_waitcnt vmcnt(5)
	s_waitcnt lgkmcnt(0)
	s_barrier
	ds_read_b128 v[72:75], v4 offset:8192
	ds_read_b128 v[8:11], v6 offset:18432
	ds_read_b128 v[48:51], v45 offset:49152
	ds_read_b128 v[56:59], v45 offset:57344
	ds_read_b128 v[12:15], v6 offset:18496
	ds_read_b128 v[60:63], v46 offset:57344
	ds_read_b128 v[52:55], v46 offset:49152
	ds_read_b128 v[16:19], v6 offset:20736
	ds_read_b128 v[20:23], v6 offset:20800
	ds_read_b64 v[64:65], v47 offset:49152
	ds_read_b64 v[66:67], v47 offset:51200
	ds_read_b64 v[68:69], v5 offset:16384
	ds_read_b64 v[70:71], v44 offset:16384
	s_movk_i32 s42, 16384
	s_cmp_lt_u32 s4, 4
	s_cbranch_scc0 .Lrws3_gen_late2
	s_waitcnt lgkmcnt(12)
	s_cmp_eq_u32 s16, s64
	s_cbranch_scc1 .Lrws3_gen_skipst2
	global_store_dwordx4 v3, v[72:75], s[6:7]
	s_add_u32 s6, s6, s48
	s_addc_u32 s7, s7, s49

; #define LAS __attribute__((address_space(3)))
; __device__ __forceinline__ unsigned pk2(float lo, float hi) { f32x2 f = {lo, hi}; bf16x2_t v = __builtin_convertvector(f, bf16x2_t); return __builtin_bit_cast(unsigned, v); }
; __device__ __forceinline__ void rwkv_seq(LAS unsigned char* lds, const MixBufs& B, const bf16_t* rq, int L, int seq, int h, int d) {
;     ...
;         for (int tt = 0; tt < 2; ++tt) {
;             const int tn = tn0 + tt;
;             const bf16x8 b0 = *(const LAS bf16x8*)(cur + (tn * 16 + r) * RL + q * 8), b1 = *(const LAS bf16x8*)(cur + (tn * 16 + r) * RL + 32 + q * 8);
;             f32x4 y = (f32x4){0.f, 0.f, 0.f, 0.f}, hn = (f32x4){0.f, 0.f, 0.f, 0.f};
;             y = __builtin_amdgcn_mfma_f32_16x16x32_bf16(b0, qa0, y, 0, 0, 0); y = __builtin_amdgcn_mfma_f32_16x16x32_bf16(b1, qa1, y, 0, 0, 0);
;             hn = __builtin_amdgcn_mfma_f32_16x16x32_bf16(pa0, b0, hn, 0, 0, 0); hn = __builtin_amdgcn_mfma_f32_16x16x32_bf16(pa1, b1, hn, 0, 0, 0);
;             const u32x2 hl = tt == 0 ? hl0 : hl1;
;             hn[0] += __uint_as_float(hl.x << 16); hn[1] += __uint_as_float(hl.x & 0xffff0000u); hn[2] += __uint_as_float(hl.y << 16); hn[3] += __uint_as_float(hl.y & 0xffff0000u);
;             u32x2 o; o.x = pk2(hn[0], hn[1]); o.y = pk2(hn[2], hn[3]);
;             *(LAS u32x2*)(nxt + (tn * 16 + r) * RL + tm * 16 + q * 4) = o;
;             { const u32x2 yo = yl[tt];
;               y[0] += __uint_as_float(yo.x << 16); y[1] += __uint_as_float(yo.x & 0xffff0000u); y[2] += __uint_as_float(yo.y << 16); y[3] += __uint_as_float(yo.y & 0xffff0000u);
;               u32x2 o2; o2.x = pk2(y[0], y[1]); o2.y = pk2(y[2], y[3]); *(u32x2*)(yrow + tn * 16) = o2; }
.Lrws3_gen_late2:
	s_waitcnt lgkmcnt(9)
	v_mfma_f32_16x16x32_bf16 v[24:27], v[8:11], v[48:51], 0
	v_mfma_f32_16x16x32_bf16 v[28:31], v[56:59], v[8:11], 0
	s_waitcnt lgkmcnt(6)
	v_mfma_f32_16x16x32_bf16 v[28:31], v[60:63], v[12:15], v[28:31]
	v_mfma_f32_16x16x32_bf16 v[24:27], v[12:15], v[52:55], v[24:27]
	s_waitcnt lgkmcnt(5)
	v_mfma_f32_16x16x32_bf16 v[36:39], v[56:59], v[16:19], 0
	v_mfma_f32_16x16x32_bf16 v[32:35], v[16:19], v[48:51], 0
	s_waitcnt lgkmcnt(4)
	v_mfma_f32_16x16x32_bf16 v[36:39], v[60:63], v[20:23], v[36:39]
	v_mfma_f32_16x16x32_bf16 v[32:35], v[20:23], v[52:55], v[32:35]
	s_waitcnt lgkmcnt(0)
	v_lshlrev_b32_e32 v40, 16, v64
	v_and_b32_e32 v41, 0xffff0000, v64
	v_lshlrev_b32_e32 v42, 16, v65
	v_and_b32_e32 v43, 0xffff0000, v65
	v_pk_add_f32 v[28:29], v[28:29], v[40:41]
	v_pk_add_f32 v[30:31], v[30:31], v[42:43]
	v_cvt_pk_bf16_f32 v28, v28, v29
	v_cvt_pk_bf16_f32 v29, v30, v31
	ds_write_b64 v7, v[28:29] offset:0
	v_lshlrev_b32_e32 v40, 16, v66
	v_and_b32_e32 v41, 0xffff0000, v66
	v_lshlrev_b32_e32 v42, 16, v67
	v_and_b32_e32 v43, 0xffff0000, v67
	v_pk_add_f32 v[36:37], v[36:37], v[40:41]
	v_pk_add_f32 v[38:39], v[38:39], v[42:43]
	v_cvt_pk_bf16_f32 v36, v36, v37
	v_cvt_pk_bf16_f32 v37, v38, v39
	ds_write_b64 v7, v[36:37] offset:2304
	v_lshlrev_b32_e32 v40, 16, v68
	v_and_b32_e32 v41, 0xffff0000, v68
	v_lshlrev_b32_e32 v42, 16, v69
	v_and_b32_e32 v43, 0xffff0000, v69
	v_pk_add_f32 v[24:25], v[24:25], v[40:41]
	v_pk_add_f32 v[26:27], v[26:27], v[42:43]
	v_cvt_pk_bf16_f32 v24, v24, v25
	v_cvt_pk_bf16_f32 v25, v26, v27
	ds_write_b64 v5, v[24:25] offset:16384
	v_lshlrev_b32_e32 v40, 16, v70
	v_and_b32_e32 v41, 0xffff0000, v70
	v_lshlrev_b32_e32 v42, 16, v71
	v_and_b32_e32 v43, 0xffff0000, v71
	v_pk_add_f32 v[32:33], v[32:33], v[40:41]
	v_pk_add_f32 v[34:35], v[34:35], v[42:43]
	v_cvt_pk_bf16_f32 v32, v32, v33
	v_cvt_pk_bf16_f32 v33, v34, v35
	ds_write_b64 v44, v[32:33] offset:16384
	s_cmp_lt_u32 s4, 4
	s_cbranch_scc1 .Lrws3_gen_end2
	s_cmp_eq_u32 s16, s64
	s_cbranch_scc1 .Lrws3_gen_skipst22
	global_store_dwordx4 v3, v[72:75], s[6:7]
	s_add_u32 s6, s6, s48
	s_addc_u32 s7, s7, s49

; #define LAS __attribute__((address_space(3)))
; __device__ __forceinline__ void rwkv_seq(LAS unsigned char* lds, const MixBufs& B, const bf16_t* rq, int L, int seq, int h, int d) {
;     ...
;     for (int c = 0; c < nch; ++c) {
;         const bf16_t* gn = g + (c + 1 < nch ? custride : 0);
;         const bf16x8 nqa0 = *(const bf16x8*)(gn + aoff), nqa1 = *(const bf16x8*)(gn + aoff + 32);
;         const bf16x8 npa0 = *(const bf16x8*)(gn + 4096 + aoff), npa1 = *(const bf16x8*)(gn + 4096 + aoff + 32);
;         const u32x2 nhl0 = *(const u32x2*)(gn + 8192 + (tn0 * 16 + r) * 64 + tm * 16 + q * 4), nhl1 = *(const u32x2*)(gn + 8192 + ((tn0 + 1) * 16 + r) * 64 + tm * 16 + q * 4);
;         u32x2 yl[2];
;         const int ti_ = tm * 16 + r;
;         bf16_t* yrow = yout + (size_t)(d == 0 ? base + c * 64 + ti_ : base + L - 1 - (c * 64 + ti_)) * 256 + h * 64 + q * 4;
; #pragma unroll
;         for (int tt = 0; tt < 2; ++tt) yl[tt] = *(const u32x2*)(yrow + (tn0 + tt) * 16);
;         lds_barrier();
;         const LAS bf16_t* cur = (const LAS bf16_t*)(lds + (c & 1) * 9216);
;         LAS bf16_t* nxt = (LAS bf16_t*)(lds + ((c + 1) & 1) * 9216);
; #pragma unroll
;         for (int tt = 0; tt < 2; ++tt) {
;             const int tn = tn0 + tt;
;             const bf16x8 b0 = *(const LAS bf16x8*)(cur + (tn * 16 + r) * RL + q * 8), b1 = *(const LAS bf16x8*)(cur + (tn * 16 + r) * RL + 32 + q * 8);
;             f32x4 y = (f32x4){0.f, 0.f, 0.f, 0.f}, hn = (f32x4){0.f, 0.f, 0.f, 0.f};
;             y = __builtin_amdgcn_mfma_f32_16x16x32_bf16(b0, qa0, y, 0, 0, 0); y = __builtin_amdgcn_mfma_f32_16x16x32_bf16(b1, qa1, y, 0, 0, 0);
;             hn = __builtin_amdgcn_mfma_f32_16x16x32_bf16(pa0, b0, hn, 0, 0, 0); hn = __builtin_amdgcn_mfma_f32_16x16x32_bf16(pa1, b1, hn, 0, 0, 0);
;             const u32x2 hl = tt == 0 ? hl0 : hl1;
;             hn[0] += __uint_as_float(hl.x << 16); hn[1] += __uint_as_float(hl.x & 0xffff0000u); hn[2] += __uint_as_float(hl.y << 16); hn[3] += __uint_as_float(hl.y & 0xffff0000u);
;             u32x2 o; o.x = pk2(hn[0], hn[1]); o.y = pk2(hn[2], hn[3]);
;             *(LAS u32x2*)(nxt + (tn * 16 + r) * RL + tm * 16 + q * 4) = o;
;             { const u32x2 yo = yl[tt];
;               y[0] += __uint_as_float(yo.x << 16); y[1] += __uint_as_float(yo.x & 0xffff0000u); y[2] += __uint_as_float(yo.y << 16); y[3] += __uint_as_float(yo.y & 0xffff0000u);
.Lrws3_gen_end2:
	s_add_i32 s16, s16, -1
	s_cmp_eq_u32 s16, 0
	s_cbranch_scc1 .Lrws3_gen_exit
	s_branch .Lrws3_gen_loop
